# SWA loop: -mref kept in a 16-register tile used as the C operand of the first QK MFMAs (removes two init MFMAs per key tile; bitwise identical), on top of the same change in the MLA loop
# speedup vs baseline: 1.0130x; 1.0036x over previous
.LBB0_462:
	v_xor_b32_e32 v218, 0x80000000, v114
	v_mov_b32_e32 v219, v218
	v_mov_b32_e32 v220, v218
	v_mov_b32_e32 v221, v218
	v_mov_b32_e32 v222, v218
	v_mov_b32_e32 v223, v218
	v_mov_b32_e32 v224, v218
	v_mov_b32_e32 v225, v218
	v_mov_b32_e32 v226, v218
	v_mov_b32_e32 v227, v218
	v_mov_b32_e32 v228, v218
	v_mov_b32_e32 v229, v218
	v_mov_b32_e32 v230, v218
	v_mov_b32_e32 v231, v218
	v_mov_b32_e32 v232, v218
	v_mov_b32_e32 v233, v218

.LBB0_464:
	s_cmp_ge_i32 s10, s24
	s_cselect_b64 s[10:11], -1, 0
	s_xor_b64 s[62:63], s[30:31], -1
	s_or_b64 s[10:11], s[62:63], s[10:11]
	s_and_b64 vcc, exec, s[10:11]
	s_waitcnt lgkmcnt(6)
	v_mfma_f32_32x32x16_bf16 v[34:49], v[148:151], v[66:69], v[218:233]
	v_mfma_f32_32x32x16_bf16 v[50:65], v[152:155], v[66:69], v[218:233]
	s_waitcnt lgkmcnt(4)
	v_mfma_f32_32x32x16_bf16 v[34:49], v[156:159], v[70:73], v[34:49]
	v_mfma_f32_32x32x16_bf16 v[50:65], v[160:163], v[70:73], v[50:65]
	s_waitcnt lgkmcnt(2)
	v_mfma_f32_32x32x16_bf16 v[34:49], v[164:167], v[74:77], v[34:49]
	v_mfma_f32_32x32x16_bf16 v[50:65], v[168:171], v[74:77], v[50:65]
	s_waitcnt lgkmcnt(0)
	v_mfma_f32_32x32x16_bf16 v[34:49], v[172:175], v[78:81], v[34:49]
	v_mfma_f32_32x32x16_bf16 v[50:65], v[176:179], v[78:81], v[50:65]
	ds_read_b64_tr_b16 v[180:181], v234 offset:13312
	ds_read_b64_tr_b16 v[182:183], v234 offset:14848
	ds_read_b64_tr_b16 v[184:185], v234 offset:16384
	ds_read_b64_tr_b16 v[186:187], v234 offset:17920
	ds_read_b64_tr_b16 v[188:189], v234 offset:19456
	ds_read_b64_tr_b16 v[190:191], v234 offset:20992
	ds_read_b64_tr_b16 v[192:193], v234 offset:22528
	ds_read_b64_tr_b16 v[194:195], v234 offset:24064
	s_cbranch_vccnz .LBB0_466
	v_add_u32_e32 v0, 59, v110
	v_cmp_lt_u32_e32 vcc, s6, v0
	v_add_u32_e32 v0, 27, v110
	s_nop 4
	v_cndmask_b32_e32 v34, v248, v34, vcc
	v_cmp_lt_u32_e32 vcc, s6, v0
	v_add_u32_e32 v0, 58, v110
	s_nop 0
	v_cndmask_b32_e32 v50, v248, v50, vcc
	v_cmp_lt_u32_e32 vcc, s6, v0
	v_add_u32_e32 v0, 26, v110
	s_nop 0
	v_cndmask_b32_e32 v35, v248, v35, vcc
	v_cmp_lt_u32_e32 vcc, s6, v0
	v_add_u32_e32 v0, 57, v110
	s_nop 0
	v_cndmask_b32_e32 v51, v248, v51, vcc
	v_cmp_lt_u32_e32 vcc, s6, v0
	v_add_u32_e32 v0, 25, v110
	s_nop 0
	v_cndmask_b32_e32 v36, v248, v36, vcc
	v_cmp_lt_u32_e32 vcc, s6, v0
	v_add_u32_e32 v0, 56, v110
	s_nop 0
	v_cndmask_b32_e32 v52, v248, v52, vcc
	v_cmp_lt_u32_e32 vcc, s6, v0
	v_add_u32_e32 v0, 24, v110
	s_nop 0
	v_cndmask_b32_e32 v37, v248, v37, vcc
	v_cmp_lt_u32_e32 vcc, s6, v0
	v_add_u32_e32 v0, 51, v110
	s_nop 0
	v_cndmask_b32_e32 v53, v248, v53, vcc
	v_cmp_lt_u32_e32 vcc, s6, v0
	v_add_u32_e32 v0, 19, v110
	s_nop 0
	v_cndmask_b32_e32 v38, v248, v38, vcc
	v_cmp_lt_u32_e32 vcc, s6, v0
	v_add_u32_e32 v0, 50, v110
	s_nop 0
	v_cndmask_b32_e32 v54, v248, v54, vcc
	v_cmp_lt_u32_e32 vcc, s6, v0
	v_add_u32_e32 v0, 18, v110
	s_nop 0
	v_cndmask_b32_e32 v39, v248, v39, vcc
	v_cmp_lt_u32_e32 vcc, s6, v0
	v_add_u32_e32 v0, 49, v110
	s_nop 0
	v_cndmask_b32_e32 v55, v248, v55, vcc
	v_cmp_lt_u32_e32 vcc, s6, v0
	v_add_u32_e32 v0, 17, v110
	s_nop 0
	v_cndmask_b32_e32 v40, v248, v40, vcc
	v_cmp_lt_u32_e32 vcc, s6, v0
	v_add_u32_e32 v0, 48, v110
	s_nop 0
	v_cndmask_b32_e32 v56, v248, v56, vcc
	v_cmp_lt_u32_e32 vcc, s6, v0
	v_add_u32_e32 v0, 16, v110
	s_nop 0
	v_cndmask_b32_e32 v41, v248, v41, vcc
	v_cmp_lt_u32_e32 vcc, s6, v0
	v_add_u32_e32 v0, 43, v110
	s_nop 0
	v_cndmask_b32_e32 v57, v248, v57, vcc
	v_cmp_lt_u32_e32 vcc, s6, v0
	v_add_u32_e32 v0, 11, v110
	s_nop 0
	v_cndmask_b32_e32 v42, v248, v42, vcc
	v_cmp_lt_u32_e32 vcc, s6, v0
	v_add_u32_e32 v0, 42, v110
	s_nop 0
	v_cndmask_b32_e32 v58, v248, v58, vcc
	v_cmp_lt_u32_e32 vcc, s6, v0
	v_add_u32_e32 v0, 10, v110
	s_nop 0
	v_cndmask_b32_e32 v43, v248, v43, vcc
	v_cmp_lt_u32_e32 vcc, s6, v0
	v_add_u32_e32 v0, 41, v110
	s_nop 0
	v_cndmask_b32_e32 v59, v248, v59, vcc
	v_cmp_lt_u32_e32 vcc, s6, v0
	v_add_u32_e32 v0, 9, v110
	s_nop 0
	v_cndmask_b32_e32 v44, v248, v44, vcc
	v_cmp_lt_u32_e32 vcc, s6, v0
	v_add_u32_e32 v0, 40, v110
	s_nop 0
	v_cndmask_b32_e32 v60, v248, v60, vcc
	v_cmp_lt_u32_e32 vcc, s6, v0
	v_add_u32_e32 v0, 8, v110
	s_nop 0
	v_cndmask_b32_e32 v45, v248, v45, vcc
	v_cmp_lt_u32_e32 vcc, s6, v0
	v_add_u32_e32 v0, 35, v110
	s_nop 0
	v_cndmask_b32_e32 v61, v248, v61, vcc
	v_cmp_lt_u32_e32 vcc, s6, v0
	v_add_u32_e32 v0, 3, v110
	s_nop 0
	v_cndmask_b32_e32 v46, v248, v46, vcc
	v_cmp_lt_u32_e32 vcc, s6, v0
	v_add_u32_e32 v0, 34, v110
	s_nop 0
	v_cndmask_b32_e32 v62, v248, v62, vcc
	v_cmp_lt_u32_e32 vcc, s6, v0
	v_add_u32_e32 v0, 2, v110
	s_nop 0
	v_cndmask_b32_e32 v47, v248, v47, vcc
	v_cmp_lt_u32_e32 vcc, s6, v0
	v_add_u32_e32 v0, 33, v110
	s_nop 0
	v_cndmask_b32_e32 v63, v248, v63, vcc
	v_cmp_lt_u32_e32 vcc, s6, v0
	v_add_u32_e32 v0, 1, v110
	s_nop 0
	v_cndmask_b32_e32 v48, v248, v48, vcc
	v_cmp_lt_u32_e32 vcc, s6, v0
	v_add_u32_e32 v0, 32, v110
	s_nop 0
	v_cndmask_b32_e32 v64, v248, v64, vcc
	v_cmp_lt_u32_e32 vcc, s6, v0
	s_nop 1
	v_cndmask_b32_e32 v49, v248, v49, vcc
	v_cmp_lt_u32_e32 vcc, s6, v110
	s_nop 1
	v_cndmask_b32_e32 v65, v248, v65, vcc

.LBB0_469:
	s_or_b64 exec, exec, s[10:11]
	v_xor_b32_e32 v218, 0x80000000, v0
	v_mov_b32_e32 v219, v218
	v_mov_b32_e32 v220, v218
	v_mov_b32_e32 v221, v218
	v_mov_b32_e32 v222, v218
	v_mov_b32_e32 v223, v218
	v_mov_b32_e32 v224, v218
	v_mov_b32_e32 v225, v218
	v_mov_b32_e32 v226, v218
	v_mov_b32_e32 v227, v218
	v_mov_b32_e32 v228, v218
	v_mov_b32_e32 v229, v218
	v_mov_b32_e32 v230, v218
	v_mov_b32_e32 v231, v218
	v_mov_b32_e32 v232, v218
	v_mov_b32_e32 v233, v218
	v_sub_f32_e32 v114, v0, v114
	v_exp_f32_e64 v116, -v114
	v_pk_add_f32 v[34:35], v[34:35], v[114:115] op_sel_hi:[1,0] neg_lo:[0,1] neg_hi:[0,1]
	v_pk_add_f32 v[50:51], v[50:51], v[114:115] op_sel_hi:[1,0] neg_lo:[0,1] neg_hi:[0,1]
	v_pk_add_f32 v[36:37], v[36:37], v[114:115] op_sel_hi:[1,0] neg_lo:[0,1] neg_hi:[0,1]
	v_pk_add_f32 v[52:53], v[52:53], v[114:115] op_sel_hi:[1,0] neg_lo:[0,1] neg_hi:[0,1]
	v_pk_add_f32 v[38:39], v[38:39], v[114:115] op_sel_hi:[1,0] neg_lo:[0,1] neg_hi:[0,1]
	v_pk_add_f32 v[54:55], v[54:55], v[114:115] op_sel_hi:[1,0] neg_lo:[0,1] neg_hi:[0,1]
	v_pk_add_f32 v[40:41], v[40:41], v[114:115] op_sel_hi:[1,0] neg_lo:[0,1] neg_hi:[0,1]
	v_pk_add_f32 v[56:57], v[56:57], v[114:115] op_sel_hi:[1,0] neg_lo:[0,1] neg_hi:[0,1]
	v_pk_add_f32 v[42:43], v[42:43], v[114:115] op_sel_hi:[1,0] neg_lo:[0,1] neg_hi:[0,1]
	v_pk_add_f32 v[58:59], v[58:59], v[114:115] op_sel_hi:[1,0] neg_lo:[0,1] neg_hi:[0,1]
	v_pk_add_f32 v[44:45], v[44:45], v[114:115] op_sel_hi:[1,0] neg_lo:[0,1] neg_hi:[0,1]
	v_pk_add_f32 v[60:61], v[60:61], v[114:115] op_sel_hi:[1,0] neg_lo:[0,1] neg_hi:[0,1]
	v_pk_add_f32 v[46:47], v[46:47], v[114:115] op_sel_hi:[1,0] neg_lo:[0,1] neg_hi:[0,1]
	v_pk_add_f32 v[62:63], v[62:63], v[114:115] op_sel_hi:[1,0] neg_lo:[0,1] neg_hi:[0,1]
	v_pk_add_f32 v[48:49], v[48:49], v[114:115] op_sel_hi:[1,0] neg_lo:[0,1] neg_hi:[0,1]
	v_pk_add_f32 v[64:65], v[64:65], v[114:115] op_sel_hi:[1,0] neg_lo:[0,1] neg_hi:[0,1]
	v_pk_mul_f32 v[32:33], v[32:33], v[116:117] op_sel_hi:[1,0]
	v_pk_mul_f32 v[30:31], v[30:31], v[116:117] op_sel_hi:[1,0]
	v_pk_mul_f32 v[28:29], v[28:29], v[116:117] op_sel_hi:[1,0]
	v_pk_mul_f32 v[26:27], v[26:27], v[116:117] op_sel_hi:[1,0]
	v_pk_mul_f32 v[24:25], v[24:25], v[116:117] op_sel_hi:[1,0]
	v_pk_mul_f32 v[22:23], v[22:23], v[116:117] op_sel_hi:[1,0]
	v_pk_mul_f32 v[20:21], v[20:21], v[116:117] op_sel_hi:[1,0]
	v_pk_mul_f32 v[18:19], v[18:19], v[116:117] op_sel_hi:[1,0]
	v_pk_mul_f32 v[16:17], v[16:17], v[116:117] op_sel_hi:[1,0]
	v_pk_mul_f32 v[14:15], v[14:15], v[116:117] op_sel_hi:[1,0]
	v_pk_mul_f32 v[12:13], v[12:13], v[116:117] op_sel_hi:[1,0]
	v_pk_mul_f32 v[10:11], v[10:11], v[116:117] op_sel_hi:[1,0]
	v_pk_mul_f32 v[8:9], v[8:9], v[116:117] op_sel_hi:[1,0]
	v_pk_mul_f32 v[6:7], v[6:7], v[116:117] op_sel_hi:[1,0]
	v_pk_mul_f32 v[4:5], v[4:5], v[116:117] op_sel_hi:[1,0]
	v_pk_mul_f32 v[2:3], v[2:3], v[116:117] op_sel_hi:[1,0]
	v_mul_f32_e32 v101, v101, v116
	s_branch .LBB0_471
